# v044 + RG-LRU carry composition unrolled (7 LDS entries read up front instead of one exposed LDS round trip per step)
# speedup vs baseline: 1.0073x; 1.0045x over previous
.LBB0_268:
	v_add_u32_e32 v94, 0xfffffa00, v94
	ds_read_b64 v[224:225], v94 offset:1536
	ds_read_b64 v[226:227], v94 offset:1280
	ds_read_b64 v[228:229], v94 offset:1024
	ds_read_b64 v[230:231], v94 offset:768
	ds_read_b64 v[232:233], v94 offset:512
	ds_read_b64 v[234:235], v94 offset:256
	ds_read_b64 v[236:237], v94
	s_waitcnt lgkmcnt(6)
	v_mul_f32_e32 v8, v8, v224
	v_fma_f32 v1, v1, v224, v225
	s_cmp_ge_i32 s64, 6
	s_cbranch_scc1 .Lscan_done_7
	s_waitcnt lgkmcnt(5)
	v_mul_f32_e32 v8, v8, v226
	v_fma_f32 v1, v1, v226, v227
	s_cmp_ge_i32 s64, 5
	s_cbranch_scc1 .Lscan_done_7
	s_waitcnt lgkmcnt(4)
	v_mul_f32_e32 v8, v8, v228
	v_fma_f32 v1, v1, v228, v229
	s_cmp_ge_i32 s64, 4
	s_cbranch_scc1 .Lscan_done_7
	s_waitcnt lgkmcnt(3)
	v_mul_f32_e32 v8, v8, v230
	v_fma_f32 v1, v1, v230, v231
	s_cmp_ge_i32 s64, 3
	s_cbranch_scc1 .Lscan_done_7
	s_waitcnt lgkmcnt(2)
	v_mul_f32_e32 v8, v8, v232
	v_fma_f32 v1, v1, v232, v233
	s_cmp_ge_i32 s64, 2
	s_cbranch_scc1 .Lscan_done_7
	s_waitcnt lgkmcnt(1)
	v_mul_f32_e32 v8, v8, v234
	v_fma_f32 v1, v1, v234, v235
	s_cmp_ge_i32 s64, 1
	s_cbranch_scc1 .Lscan_done_7
	s_waitcnt lgkmcnt(0)
	v_mul_f32_e32 v8, v8, v236
	v_fma_f32 v1, v1, v236, v237
.Lscan_done_7:
	s_waitcnt lgkmcnt(0)
	s_branch .LBB0_270

.LBB0_276:
	v_add_u32_e32 v148, 0xfffffa00, v148
	ds_read_b64 v[224:225], v148 offset:1536
	ds_read_b64 v[226:227], v148 offset:1280
	ds_read_b64 v[228:229], v148 offset:1024
	ds_read_b64 v[230:231], v148 offset:768
	ds_read_b64 v[232:233], v148 offset:512
	ds_read_b64 v[234:235], v148 offset:256
	ds_read_b64 v[236:237], v148
	s_waitcnt lgkmcnt(6)
	v_mul_f32_e32 v8, v8, v224
	v_fma_f32 v1, v1, v224, v225
	s_cmp_ge_i32 s64, 6
	s_cbranch_scc1 .Lscan_done_6
	s_waitcnt lgkmcnt(5)
	v_mul_f32_e32 v8, v8, v226
	v_fma_f32 v1, v1, v226, v227
	s_cmp_ge_i32 s64, 5
	s_cbranch_scc1 .Lscan_done_6
	s_waitcnt lgkmcnt(4)
	v_mul_f32_e32 v8, v8, v228
	v_fma_f32 v1, v1, v228, v229
	s_cmp_ge_i32 s64, 4
	s_cbranch_scc1 .Lscan_done_6
	s_waitcnt lgkmcnt(3)
	v_mul_f32_e32 v8, v8, v230
	v_fma_f32 v1, v1, v230, v231
	s_cmp_ge_i32 s64, 3
	s_cbranch_scc1 .Lscan_done_6
	s_waitcnt lgkmcnt(2)
	v_mul_f32_e32 v8, v8, v232
	v_fma_f32 v1, v1, v232, v233
	s_cmp_ge_i32 s64, 2
	s_cbranch_scc1 .Lscan_done_6
	s_waitcnt lgkmcnt(1)
	v_mul_f32_e32 v8, v8, v234
	v_fma_f32 v1, v1, v234, v235
	s_cmp_ge_i32 s64, 1
	s_cbranch_scc1 .Lscan_done_6
	s_waitcnt lgkmcnt(0)
	v_mul_f32_e32 v8, v8, v236
	v_fma_f32 v1, v1, v236, v237

.LBB0_292:
	v_add_u32_e32 v49, 0xfffffa00, v49
	ds_read_b64 v[224:225], v49 offset:1536
	ds_read_b64 v[226:227], v49 offset:1280
	ds_read_b64 v[228:229], v49 offset:1024
	ds_read_b64 v[230:231], v49 offset:768
	ds_read_b64 v[232:233], v49 offset:512
	ds_read_b64 v[234:235], v49 offset:256
	ds_read_b64 v[236:237], v49
	s_waitcnt lgkmcnt(6)
	v_mul_f32_e32 v8, v8, v224
	v_fma_f32 v1, v1, v224, v225
	s_cmp_ge_i32 s64, 6
	s_cbranch_scc1 .Lscan_done_4
	s_waitcnt lgkmcnt(5)
	v_mul_f32_e32 v8, v8, v226
	v_fma_f32 v1, v1, v226, v227
	s_cmp_ge_i32 s64, 5
	s_cbranch_scc1 .Lscan_done_4
	s_waitcnt lgkmcnt(4)
	v_mul_f32_e32 v8, v8, v228
	v_fma_f32 v1, v1, v228, v229
	s_cmp_ge_i32 s64, 4
	s_cbranch_scc1 .Lscan_done_4
	s_waitcnt lgkmcnt(3)
	v_mul_f32_e32 v8, v8, v230
	v_fma_f32 v1, v1, v230, v231
	s_cmp_ge_i32 s64, 3
	s_cbranch_scc1 .Lscan_done_4
	s_waitcnt lgkmcnt(2)
	v_mul_f32_e32 v8, v8, v232
	v_fma_f32 v1, v1, v232, v233
	s_cmp_ge_i32 s64, 2
	s_cbranch_scc1 .Lscan_done_4
	s_waitcnt lgkmcnt(1)
	v_mul_f32_e32 v8, v8, v234
	v_fma_f32 v1, v1, v234, v235
	s_cmp_ge_i32 s64, 1
	s_cbranch_scc1 .Lscan_done_4
	s_waitcnt lgkmcnt(0)
	v_mul_f32_e32 v8, v8, v236
	v_fma_f32 v1, v1, v236, v237

.LBB0_330:
	ds_read_b64 v[224:225], v1
	ds_read_b64 v[226:227], v1 offset:256
	ds_read_b64 v[228:229], v1 offset:512
	ds_read_b64 v[230:231], v1 offset:768
	ds_read_b64 v[232:233], v1 offset:1024
	ds_read_b64 v[234:235], v1 offset:1280
	ds_read_b64 v[236:237], v1 offset:1536
	s_waitcnt lgkmcnt(6)
	v_mul_f32_e32 v0, v0, v224
	v_fma_f32 v3, v3, v224, v225
	s_cmp_eq_u32 s5, 1
	s_cbranch_scc1 .Lscan_done_3
	s_waitcnt lgkmcnt(5)
	v_mul_f32_e32 v0, v0, v226
	v_fma_f32 v3, v3, v226, v227
	s_cmp_eq_u32 s5, 2
	s_cbranch_scc1 .Lscan_done_3
	s_waitcnt lgkmcnt(4)
	v_mul_f32_e32 v0, v0, v228
	v_fma_f32 v3, v3, v228, v229
	s_cmp_eq_u32 s5, 3
	s_cbranch_scc1 .Lscan_done_3
	s_waitcnt lgkmcnt(3)
	v_mul_f32_e32 v0, v0, v230
	v_fma_f32 v3, v3, v230, v231
	s_cmp_eq_u32 s5, 4
	s_cbranch_scc1 .Lscan_done_3
	s_waitcnt lgkmcnt(2)
	v_mul_f32_e32 v0, v0, v232
	v_fma_f32 v3, v3, v232, v233
	s_cmp_eq_u32 s5, 5
	s_cbranch_scc1 .Lscan_done_3
	s_waitcnt lgkmcnt(1)
	v_mul_f32_e32 v0, v0, v234
	v_fma_f32 v3, v3, v234, v235
	s_cmp_eq_u32 s5, 6
	s_cbranch_scc1 .Lscan_done_3
	s_waitcnt lgkmcnt(0)
	v_mul_f32_e32 v0, v0, v236
	v_fma_f32 v3, v3, v236, v237
.Lscan_done_3:
	s_waitcnt lgkmcnt(0)
.LBB0_331:
	v_lshl_add_u64 v[126:127], s[36:37], 0, v[88:89]
	v_lshl_add_u64 v[128:129], s[40:41], 0, v[88:89]
	v_lshl_add_u64 v[130:131], s[42:43], 0, v[88:89]
	v_cndmask_b32_e64 v1, v13, 1.0, s[0:1]
	v_cndmask_b32_e64 v2, v10, 0, s[0:1]
	v_cndmask_b32_e64 v10, v42, v15, s[0:1]
	v_cndmask_b32_e64 v13, v17, v14, s[0:1]
	v_cndmask_b32_e64 v14, v46, v43, s[0:1]
	v_cndmask_b32_e64 v15, v44, v41, s[0:1]
	s_ashr_i32 s9, s8, 31
	v_lshlrev_b32_e32 v88, 2, v94
	v_cndmask_b32_e64 v17, v96, v47, s[0:1]
	v_cndmask_b32_e64 v41, v91, v45, s[0:1]
	v_fmac_f32_e32 v18, v32, v2
	v_mul_f32_e32 v32, v1, v32
	v_fmac_f32_e32 v31, v33, v2
	v_mul_f32_e32 v33, v1, v33
	v_fmac_f32_e32 v30, v34, v2
	v_mul_f32_e32 v34, v1, v34
	v_fmac_f32_e32 v29, v35, v2
	v_mul_f32_e32 v1, v1, v35
	v_fmac_f32_e32 v19, v20, v13
	v_mul_f32_e32 v2, v20, v10
	v_fmac_f32_e32 v28, v36, v13
	v_mul_f32_e32 v20, v36, v10
	v_fmac_f32_e32 v27, v37, v13
	v_mul_f32_e32 v35, v37, v10
	v_fmac_f32_e32 v26, v38, v13
	v_mul_f32_e32 v10, v38, v10
	v_fmac_f32_e32 v23, v12, v15
	v_mul_f32_e32 v38, v12, v14
	v_lshl_add_u64 v[12:13], s[22:23], 0, v[88:89]
	s_lshl_b64 s[4:5], s[8:9], 12
	v_fmac_f32_e32 v24, v40, v15
	v_mul_f32_e32 v37, v40, v14
	v_fmac_f32_e32 v7, v4, v41
	v_mul_f32_e32 v40, v4, v17
	v_lshl_add_u64 v[94:95], v[12:13], 0, s[4:5]
	v_lshlrev_b32_e32 v12, 14, v93
	v_mul_f32_e32 v4, v32, v0
	v_mov_b32_e32 v13, v89
	v_fmac_f32_e32 v18, v32, v3
	v_cvt_pk_bf16_f32 v4, v18, v4
	v_lshl_add_u64 v[96:97], v[94:95], 0, v[12:13]
	global_load_dword v172, v[130:131], off offset:128
	global_load_dword v173, v[126:127], off offset:128
	global_load_dword v174, v[128:129], off offset:128
	global_store_dword v[96:97], v4, off nt
	v_mul_f32_e32 v4, v33, v0
	v_or_b32_e32 v88, 0x1000, v12
	v_fmac_f32_e32 v21, v22, v15
	v_mul_f32_e32 v22, v22, v14
	v_fmac_f32_e32 v25, v39, v15
	v_mul_f32_e32 v36, v39, v14
	v_fmac_f32_e32 v31, v33, v3
	v_cvt_pk_bf16_f32 v4, v31, v4
	v_lshl_add_u64 v[14:15], v[94:95], 0, v[88:89]
	v_or_b32_e32 v98, 0x2000, v12
	v_mov_b32_e32 v99, v89
	global_store_dword v[14:15], v4, off nt
	v_mul_f32_e32 v4, v34, v0
	v_lshl_add_u64 v[14:15], v[94:95], 0, v[98:99]
	v_fmac_f32_e32 v29, v1, v3
	v_mul_f32_e32 v1, v1, v0
	v_or_b32_e32 v100, 0x3000, v12
	v_mov_b32_e32 v101, v89
	v_fmac_f32_e32 v30, v34, v3
	v_cvt_pk_bf16_f32 v4, v30, v4
	global_store_dword v[14:15], v4, off nt
	v_cvt_pk_bf16_f32 v1, v29, v1
	v_lshl_add_u64 v[14:15], v[94:95], 0, v[100:101]
	global_store_dword v[14:15], v1, off nt
	v_mul_f32_e32 v1, v2, v0
	v_or_b32_e32 v102, 0x8000, v12
	v_mov_b32_e32 v103, v89
	v_fmac_f32_e32 v19, v2, v3
	v_cvt_pk_bf16_f32 v1, v19, v1
	v_lshl_add_u64 v[14:15], v[94:95], 0, v[102:103]
	global_store_dword v[14:15], v1, off nt
	v_mul_f32_e32 v1, v20, v0
	v_or_b32_e32 v104, 0x9000, v12
	v_mov_b32_e32 v105, v89
	v_fmac_f32_e32 v28, v20, v3
	v_cvt_pk_bf16_f32 v1, v28, v1
	v_lshl_add_u64 v[14:15], v[94:95], 0, v[104:105]
	global_store_dword v[14:15], v1, off nt
	v_mul_f32_e32 v1, v35, v0
	v_or_b32_e32 v106, 0xa000, v12
	v_mov_b32_e32 v107, v89
	v_fmac_f32_e32 v27, v35, v3
	v_cvt_pk_bf16_f32 v1, v27, v1
	v_lshl_add_u64 v[14:15], v[94:95], 0, v[106:107]
	global_store_dword v[14:15], v1, off nt
	v_mul_f32_e32 v1, v10, v0
	v_or_b32_e32 v108, 0xb000, v12
	v_mov_b32_e32 v109, v89
	v_fmac_f32_e32 v26, v10, v3
	v_cvt_pk_bf16_f32 v1, v26, v1
	v_lshl_add_u64 v[14:15], v[94:95], 0, v[108:109]
	global_store_dword v[14:15], v1, off nt
	v_mul_f32_e32 v1, v22, v0
	v_or_b32_e32 v110, 0x10000, v12
	v_mov_b32_e32 v111, v89
	v_fmac_f32_e32 v21, v22, v3
	v_cvt_pk_bf16_f32 v1, v21, v1
	v_lshl_add_u64 v[14:15], v[94:95], 0, v[110:111]
	global_store_dword v[14:15], v1, off nt
	v_mul_f32_e32 v1, v36, v0
	v_or_b32_e32 v112, 0x11000, v12
	v_mov_b32_e32 v113, v89
	v_fmac_f32_e32 v25, v36, v3
	v_cvt_pk_bf16_f32 v1, v25, v1
	v_lshl_add_u64 v[14:15], v[94:95], 0, v[112:113]
	global_store_dword v[14:15], v1, off nt
	v_mul_f32_e32 v1, v37, v0
	v_or_b32_e32 v114, 0x12000, v12
	v_mov_b32_e32 v115, v89
	v_fmac_f32_e32 v24, v37, v3
	v_cvt_pk_bf16_f32 v1, v24, v1
	v_lshl_add_u64 v[14:15], v[94:95], 0, v[114:115]
	global_store_dword v[14:15], v1, off nt
	v_mul_f32_e32 v1, v38, v0
	v_or_b32_e32 v116, 0x13000, v12
	v_mov_b32_e32 v117, v89
	v_fmac_f32_e32 v8, v16, v41
	v_mul_f32_e32 v16, v16, v17
	v_fmac_f32_e32 v23, v38, v3
	v_cvt_pk_bf16_f32 v1, v23, v1
	v_lshl_add_u64 v[14:15], v[94:95], 0, v[116:117]
	global_store_dword v[14:15], v1, off nt
	v_fmac_f32_e32 v8, v16, v3
	v_mul_f32_e32 v1, v16, v0
	v_or_b32_e32 v118, 0x18000, v12
	v_mov_b32_e32 v119, v89
	v_fmac_f32_e32 v5, v9, v41
	v_mul_f32_e32 v39, v9, v17
	v_cvt_pk_bf16_f32 v1, v8, v1
	v_lshl_add_u64 v[8:9], v[94:95], 0, v[118:119]
	global_store_dword v[8:9], v1, off nt
	v_fmac_f32_e32 v5, v39, v3
	v_mul_f32_e32 v1, v39, v0
	v_or_b32_e32 v120, 0x19000, v12
	v_mov_b32_e32 v121, v89
	v_cvt_pk_bf16_f32 v1, v5, v1
	v_lshl_add_u64 v[4:5], v[94:95], 0, v[120:121]
	v_fmac_f32_e32 v11, v6, v41
	v_mul_f32_e32 v6, v6, v17
	s_lshl_b32 s6, s63, 11
	global_store_dword v[4:5], v1, off nt
	v_mul_f32_e32 v1, v40, v0
	v_or_b32_e32 v122, 0x1a000, v12
	v_mov_b32_e32 v123, v89
	s_or_b32 s6, s6, s70
	v_fmac_f32_e32 v7, v40, v3
	v_cvt_pk_bf16_f32 v1, v7, v1
	v_lshl_add_u64 v[4:5], v[94:95], 0, v[122:123]
	v_mul_f32_e32 v0, v6, v0
	v_or_b32_e32 v124, 0x1b000, v12
	v_mov_b32_e32 v125, v89
	v_lshl_add_u32 v142, v92, 3, 16
	v_cmp_gt_i32_e64 s[4:5], 32, v92
	v_add_u32_e32 v92, s6, v92
	global_store_dword v[4:5], v1, off nt
	v_fmac_f32_e32 v11, v6, v3
	v_cvt_pk_bf16_f32 v2, v11, v0
	v_lshl_add_u64 v[0:1], v[94:95], 0, v[124:125]
	global_store_dword v[0:1], v2, off nt
	s_and_saveexec_b64 s[6:7], s[4:5]
	s_cbranch_execz .LBB0_333
	ds_read2_b64 v[0:3], v142 offset1:32
	ds_read2_b64 v[4:7], v142 offset0:64 offset1:96
	ds_read2_b64 v[8:11], v142 offset0:128 offset1:160
	ds_read2_b64 v[12:15], v142 offset0:192 offset1:224
	v_ashrrev_i32_e32 v93, 31, v92
	s_waitcnt lgkmcnt(3)
	v_fma_f32 v16, 0, v0, v1
	v_pk_mul_f32 v[0:1], v[0:1], v[2:3]
	v_fma_f32 v2, v2, v16, v3
	s_waitcnt lgkmcnt(2)
	v_fma_f32 v2, v4, v2, v5
	v_fma_f32 v2, v6, v2, v7
	s_waitcnt lgkmcnt(1)
	v_fma_f32 v3, v8, v2, v9
	v_mov_b32_e32 v2, v0
	v_mov_b32_e32 v16, v4
	v_mov_b32_e32 v17, v10
	v_pk_mul_f32 v[0:1], v[0:1], v[4:5]
	v_pk_fma_f32 v[2:3], v[2:3], v[16:17], v[10:11]
	v_pk_mul_f32 v[0:1], v[0:1], v[6:7]
	s_waitcnt lgkmcnt(0)
	v_mov_b32_e32 v9, v12
	v_mov_b32_e32 v1, v3
	v_pk_mul_f32 v[2:3], v[0:1], v[8:9]
	v_pk_fma_f32 v[0:1], v[0:1], v[8:9], v[12:13]
	v_pk_mul_f32 v[2:3], v[2:3], v[10:11]
	v_mov_b32_e32 v4, v12
	v_mov_b32_e32 v0, v2
	v_mov_b32_e32 v5, v14
	v_pk_mul_f32 v[2:3], v[2:3], v[12:13]
	v_pk_fma_f32 v[0:1], v[0:1], v[4:5], v[14:15]
	v_pk_mul_f32 v[2:3], v[2:3], v[14:15]
	s_nop 0
	v_mov_b32_e32 v3, v1
	v_lshl_add_u64 v[0:1], v[92:93], 3, s[24:25]
	global_store_dwordx2 v[0:1], v[2:3], off

.LBB0_343:
	ds_read_b64 v[224:225], v1
	ds_read_b64 v[226:227], v1 offset:256
	ds_read_b64 v[228:229], v1 offset:512
	ds_read_b64 v[230:231], v1 offset:768
	ds_read_b64 v[232:233], v1 offset:1024
	ds_read_b64 v[234:235], v1 offset:1280
	ds_read_b64 v[236:237], v1 offset:1536
	s_waitcnt lgkmcnt(6)
	v_mul_f32_e32 v0, v0, v224
	v_fma_f32 v3, v3, v224, v225
	s_cmp_eq_u32 s9, 1
	s_cbranch_scc1 .Lscan_done_2
	s_waitcnt lgkmcnt(5)
	v_mul_f32_e32 v0, v0, v226
	v_fma_f32 v3, v3, v226, v227
	s_cmp_eq_u32 s9, 2
	s_cbranch_scc1 .Lscan_done_2
	s_waitcnt lgkmcnt(4)
	v_mul_f32_e32 v0, v0, v228
	v_fma_f32 v3, v3, v228, v229
	s_cmp_eq_u32 s9, 3
	s_cbranch_scc1 .Lscan_done_2
	s_waitcnt lgkmcnt(3)
	v_mul_f32_e32 v0, v0, v230
	v_fma_f32 v3, v3, v230, v231
	s_cmp_eq_u32 s9, 4
	s_cbranch_scc1 .Lscan_done_2
	s_waitcnt lgkmcnt(2)
	v_mul_f32_e32 v0, v0, v232
	v_fma_f32 v3, v3, v232, v233
	s_cmp_eq_u32 s9, 5
	s_cbranch_scc1 .Lscan_done_2
	s_waitcnt lgkmcnt(1)
	v_mul_f32_e32 v0, v0, v234
	v_fma_f32 v3, v3, v234, v235
	s_cmp_eq_u32 s9, 6
	s_cbranch_scc1 .Lscan_done_2
	s_waitcnt lgkmcnt(0)
	v_mul_f32_e32 v0, v0, v236
	v_fma_f32 v3, v3, v236, v237
.Lscan_done_2:
	s_waitcnt lgkmcnt(0)
.LBB0_344:
	v_cndmask_b32_e64 v1, v13, 1.0, s[0:1]
	v_cndmask_b32_e64 v2, v10, 0, s[0:1]
	v_cndmask_b32_e64 v10, v42, v15, s[0:1]
	v_cndmask_b32_e64 v13, v17, v14, s[0:1]
	v_cndmask_b32_e64 v14, v46, v43, s[0:1]
	v_cndmask_b32_e64 v15, v44, v41, s[0:1]
	v_cndmask_b32_e64 v17, v93, v47, s[0:1]
	v_cndmask_b32_e64 v41, v91, v45, s[0:1]
	v_fmac_f32_e32 v18, v32, v2
	v_mul_f32_e32 v32, v1, v32
	v_fmac_f32_e32 v31, v33, v2
	v_mul_f32_e32 v33, v1, v33
	v_fmac_f32_e32 v30, v34, v2
	v_mul_f32_e32 v34, v1, v34
	v_fmac_f32_e32 v29, v35, v2
	v_mul_f32_e32 v1, v1, v35
	v_fmac_f32_e32 v27, v37, v13
	v_mul_f32_e32 v35, v37, v10
	v_fmac_f32_e32 v24, v40, v15
	v_mul_f32_e32 v37, v40, v14
	v_fmac_f32_e32 v9, v4, v41
	v_mul_f32_e32 v40, v4, v17
	v_mul_f32_e32 v4, v32, v0
	v_fmac_f32_e32 v18, v32, v3
	v_cvt_pk_bf16_f32 v4, v18, v4
	v_fmac_f32_e32 v19, v20, v13
	v_mul_f32_e32 v2, v20, v10
	v_fmac_f32_e32 v28, v36, v13
	v_mul_f32_e32 v20, v36, v10
	v_fmac_f32_e32 v26, v38, v13
	v_mul_f32_e32 v10, v38, v10
	v_fmac_f32_e32 v23, v12, v15
	v_mul_f32_e32 v38, v12, v14
	v_lshl_add_u64 v[12:13], v[94:95], 0, s[38:39]
	global_load_dword v172, v[130:131], off offset:256
	global_load_dword v173, v[126:127], off offset:256
	global_load_dword v174, v[128:129], off offset:256
	global_store_dword v[96:97], v4, off offset:128 nt
	v_mul_f32_e32 v4, v33, v0
	v_fmac_f32_e32 v21, v22, v15
	v_mul_f32_e32 v22, v22, v14
	v_fmac_f32_e32 v25, v39, v15
	v_mul_f32_e32 v36, v39, v14
	v_fmac_f32_e32 v31, v33, v3
	v_cvt_pk_bf16_f32 v4, v31, v4
	v_lshl_add_u64 v[14:15], v[12:13], 0, v[88:89]
	global_store_dword v[14:15], v4, off nt
	v_mul_f32_e32 v4, v34, v0
	v_lshl_add_u64 v[14:15], v[12:13], 0, v[98:99]
	v_fmac_f32_e32 v29, v1, v3
	v_mul_f32_e32 v1, v1, v0
	v_fmac_f32_e32 v30, v34, v3
	v_cvt_pk_bf16_f32 v4, v30, v4
	global_store_dword v[14:15], v4, off nt
	v_cvt_pk_bf16_f32 v1, v29, v1
	v_lshl_add_u64 v[14:15], v[12:13], 0, v[100:101]
	global_store_dword v[14:15], v1, off nt
	v_mul_f32_e32 v1, v2, v0
	v_fmac_f32_e32 v19, v2, v3
	v_cvt_pk_bf16_f32 v1, v19, v1
	v_lshl_add_u64 v[14:15], v[12:13], 0, v[102:103]
	global_store_dword v[14:15], v1, off nt
	v_mul_f32_e32 v1, v20, v0
	v_fmac_f32_e32 v28, v20, v3
	v_cvt_pk_bf16_f32 v1, v28, v1
	v_lshl_add_u64 v[14:15], v[12:13], 0, v[104:105]
	global_store_dword v[14:15], v1, off nt
	v_mul_f32_e32 v1, v35, v0
	v_fmac_f32_e32 v27, v35, v3
	v_cvt_pk_bf16_f32 v1, v27, v1
	v_lshl_add_u64 v[14:15], v[12:13], 0, v[106:107]
	global_store_dword v[14:15], v1, off nt
	v_mul_f32_e32 v1, v10, v0
	v_fmac_f32_e32 v26, v10, v3
	v_cvt_pk_bf16_f32 v1, v26, v1
	v_lshl_add_u64 v[14:15], v[12:13], 0, v[108:109]
	global_store_dword v[14:15], v1, off nt
	v_mul_f32_e32 v1, v22, v0
	v_fmac_f32_e32 v21, v22, v3
	v_cvt_pk_bf16_f32 v1, v21, v1
	v_lshl_add_u64 v[14:15], v[12:13], 0, v[110:111]
	global_store_dword v[14:15], v1, off nt
	v_mul_f32_e32 v1, v36, v0
	v_fmac_f32_e32 v25, v36, v3
	v_cvt_pk_bf16_f32 v1, v25, v1
	v_lshl_add_u64 v[14:15], v[12:13], 0, v[112:113]
	global_store_dword v[14:15], v1, off nt
	v_mul_f32_e32 v1, v37, v0
	v_fmac_f32_e32 v24, v37, v3
	v_cvt_pk_bf16_f32 v1, v24, v1
	v_lshl_add_u64 v[14:15], v[12:13], 0, v[114:115]
	global_store_dword v[14:15], v1, off nt
	v_mul_f32_e32 v1, v38, v0
	v_fmac_f32_e32 v6, v16, v41
	v_mul_f32_e32 v16, v16, v17
	v_fmac_f32_e32 v23, v38, v3
	v_cvt_pk_bf16_f32 v1, v23, v1
	v_lshl_add_u64 v[14:15], v[12:13], 0, v[116:117]
	global_store_dword v[14:15], v1, off nt
	v_fmac_f32_e32 v6, v16, v3
	v_mul_f32_e32 v1, v16, v0
	v_fmac_f32_e32 v5, v7, v41
	v_mul_f32_e32 v39, v7, v17
	v_cvt_pk_bf16_f32 v1, v6, v1
	v_lshl_add_u64 v[6:7], v[12:13], 0, v[118:119]
	global_store_dword v[6:7], v1, off nt
	v_fmac_f32_e32 v5, v39, v3
	v_mul_f32_e32 v1, v39, v0
	v_cvt_pk_bf16_f32 v1, v5, v1
	v_lshl_add_u64 v[4:5], v[12:13], 0, v[120:121]
	v_fmac_f32_e32 v11, v8, v41
	v_mul_f32_e32 v8, v8, v17
	global_store_dword v[4:5], v1, off nt
	v_mul_f32_e32 v1, v40, v0
	v_fmac_f32_e32 v9, v40, v3
	v_cvt_pk_bf16_f32 v1, v9, v1
	v_lshl_add_u64 v[4:5], v[12:13], 0, v[122:123]
	v_mul_f32_e32 v0, v8, v0
	global_store_dword v[4:5], v1, off nt
	v_fmac_f32_e32 v11, v8, v3
	v_cvt_pk_bf16_f32 v2, v11, v0
	v_lshl_add_u64 v[0:1], v[12:13], 0, v[124:125]
	global_store_dword v[0:1], v2, off nt
	s_and_saveexec_b64 s[8:9], s[4:5]
	s_cbranch_execz .LBB0_346
	v_add_u32_e32 v12, 0x800, v142
	ds_read2_b64 v[0:3], v12 offset1:32
	ds_read2_b64 v[4:7], v12 offset0:64 offset1:96
	ds_read2_b64 v[8:11], v12 offset0:128 offset1:160
	ds_read2_b64 v[12:15], v12 offset0:192 offset1:224
	s_waitcnt lgkmcnt(3)
	v_fma_f32 v16, 0, v0, v1
	v_pk_mul_f32 v[0:1], v[0:1], v[2:3]
	v_fma_f32 v2, v2, v16, v3
	s_waitcnt lgkmcnt(2)
	v_fma_f32 v2, v4, v2, v5
	v_fma_f32 v2, v6, v2, v7
	s_waitcnt lgkmcnt(1)
	v_fma_f32 v3, v8, v2, v9
	v_mov_b32_e32 v2, v0
	v_mov_b32_e32 v16, v4
	v_mov_b32_e32 v17, v10
	v_pk_mul_f32 v[0:1], v[0:1], v[4:5]
	v_pk_fma_f32 v[2:3], v[2:3], v[16:17], v[10:11]
	v_pk_mul_f32 v[0:1], v[0:1], v[6:7]
	s_waitcnt lgkmcnt(0)
	v_mov_b32_e32 v9, v12
	v_mov_b32_e32 v1, v3
	v_pk_mul_f32 v[2:3], v[0:1], v[8:9]
	v_pk_fma_f32 v[0:1], v[0:1], v[8:9], v[12:13]
	v_pk_mul_f32 v[2:3], v[2:3], v[10:11]
	v_mov_b32_e32 v4, v12
	v_mov_b32_e32 v0, v2
	v_mov_b32_e32 v5, v14
	v_pk_mul_f32 v[2:3], v[2:3], v[12:13]
	v_pk_fma_f32 v[0:1], v[0:1], v[4:5], v[14:15]
	v_pk_mul_f32 v[2:3], v[2:3], v[14:15]
	v_add_u32_e32 v0, 32, v92
	v_mov_b32_e32 v3, v1
	v_ashrrev_i32_e32 v1, 31, v0
	v_lshl_add_u64 v[0:1], v[0:1], 3, s[24:25]
	global_store_dwordx2 v[0:1], v[2:3], off

.Lscan_done_1:
	s_waitcnt lgkmcnt(0)
.LBB0_357:
	v_cndmask_b32_e64 v1, v13, 1.0, s[0:1]
	v_cndmask_b32_e64 v2, v10, 0, s[0:1]
	v_cndmask_b32_e64 v10, v42, v15, s[0:1]
	v_cndmask_b32_e64 v13, v17, v14, s[0:1]
	v_cndmask_b32_e64 v14, v46, v43, s[0:1]
	v_cndmask_b32_e64 v15, v44, v41, s[0:1]
	v_cndmask_b32_e64 v17, v93, v47, s[0:1]
	v_cndmask_b32_e64 v41, v91, v45, s[0:1]
	v_fmac_f32_e32 v18, v32, v2
	v_mul_f32_e32 v32, v1, v32
	v_fmac_f32_e32 v31, v33, v2
	v_mul_f32_e32 v33, v1, v33
	v_fmac_f32_e32 v30, v34, v2
	v_mul_f32_e32 v34, v1, v34
	v_fmac_f32_e32 v29, v35, v2
	v_mul_f32_e32 v1, v1, v35
	v_fmac_f32_e32 v27, v37, v13
	v_mul_f32_e32 v35, v37, v10
	v_fmac_f32_e32 v24, v40, v15
	v_mul_f32_e32 v37, v40, v14
	v_fmac_f32_e32 v9, v4, v41
	v_mul_f32_e32 v40, v4, v17
	v_mul_f32_e32 v4, v32, v0
	v_fmac_f32_e32 v18, v32, v3
	v_cvt_pk_bf16_f32 v4, v18, v4
	v_fmac_f32_e32 v19, v20, v13
	v_mul_f32_e32 v2, v20, v10
	v_fmac_f32_e32 v28, v36, v13
	v_mul_f32_e32 v20, v36, v10
	v_fmac_f32_e32 v26, v38, v13
	v_mul_f32_e32 v10, v38, v10
	v_fmac_f32_e32 v23, v12, v15
	v_mul_f32_e32 v38, v12, v14
	v_lshl_add_u64 v[12:13], v[94:95], 0, s[48:49]
	global_load_dword v172, v[130:131], off offset:384
	global_load_dword v173, v[126:127], off offset:384
	global_load_dword v174, v[128:129], off offset:384
	global_store_dword v[96:97], v4, off offset:256 nt
	v_mul_f32_e32 v4, v33, v0
	v_fmac_f32_e32 v21, v22, v15
	v_mul_f32_e32 v22, v22, v14
	v_fmac_f32_e32 v25, v39, v15
	v_mul_f32_e32 v36, v39, v14
	v_fmac_f32_e32 v31, v33, v3
	v_cvt_pk_bf16_f32 v4, v31, v4
	v_lshl_add_u64 v[14:15], v[12:13], 0, v[88:89]
	global_store_dword v[14:15], v4, off nt
	v_mul_f32_e32 v4, v34, v0
	v_lshl_add_u64 v[14:15], v[12:13], 0, v[98:99]
	v_fmac_f32_e32 v29, v1, v3
	v_mul_f32_e32 v1, v1, v0
	v_fmac_f32_e32 v30, v34, v3
	v_cvt_pk_bf16_f32 v4, v30, v4
	global_store_dword v[14:15], v4, off nt
	v_cvt_pk_bf16_f32 v1, v29, v1
	v_lshl_add_u64 v[14:15], v[12:13], 0, v[100:101]
	global_store_dword v[14:15], v1, off nt
	v_mul_f32_e32 v1, v2, v0
	v_fmac_f32_e32 v19, v2, v3
	v_cvt_pk_bf16_f32 v1, v19, v1
	v_lshl_add_u64 v[14:15], v[12:13], 0, v[102:103]
	global_store_dword v[14:15], v1, off nt
	v_mul_f32_e32 v1, v20, v0
	v_fmac_f32_e32 v28, v20, v3
	v_cvt_pk_bf16_f32 v1, v28, v1
	v_lshl_add_u64 v[14:15], v[12:13], 0, v[104:105]
	global_store_dword v[14:15], v1, off nt
	v_mul_f32_e32 v1, v35, v0
	v_fmac_f32_e32 v27, v35, v3
	v_cvt_pk_bf16_f32 v1, v27, v1
	v_lshl_add_u64 v[14:15], v[12:13], 0, v[106:107]
	global_store_dword v[14:15], v1, off nt
	v_mul_f32_e32 v1, v10, v0
	v_fmac_f32_e32 v26, v10, v3
	v_cvt_pk_bf16_f32 v1, v26, v1
	v_lshl_add_u64 v[14:15], v[12:13], 0, v[108:109]
	global_store_dword v[14:15], v1, off nt
	v_mul_f32_e32 v1, v22, v0
	v_fmac_f32_e32 v21, v22, v3
	v_cvt_pk_bf16_f32 v1, v21, v1
	v_lshl_add_u64 v[14:15], v[12:13], 0, v[110:111]
	global_store_dword v[14:15], v1, off nt
	v_mul_f32_e32 v1, v36, v0
	v_fmac_f32_e32 v25, v36, v3
	v_cvt_pk_bf16_f32 v1, v25, v1
	v_lshl_add_u64 v[14:15], v[12:13], 0, v[112:113]
	global_store_dword v[14:15], v1, off nt
	v_mul_f32_e32 v1, v37, v0
	v_fmac_f32_e32 v24, v37, v3
	v_cvt_pk_bf16_f32 v1, v24, v1
	v_lshl_add_u64 v[14:15], v[12:13], 0, v[114:115]
	global_store_dword v[14:15], v1, off nt
	v_mul_f32_e32 v1, v38, v0
	v_fmac_f32_e32 v6, v16, v41
	v_mul_f32_e32 v16, v16, v17
	v_fmac_f32_e32 v23, v38, v3
	v_cvt_pk_bf16_f32 v1, v23, v1
	v_lshl_add_u64 v[14:15], v[12:13], 0, v[116:117]
	global_store_dword v[14:15], v1, off nt
	v_fmac_f32_e32 v6, v16, v3
	v_mul_f32_e32 v1, v16, v0
	v_fmac_f32_e32 v5, v7, v41
	v_mul_f32_e32 v39, v7, v17
	v_cvt_pk_bf16_f32 v1, v6, v1
	v_lshl_add_u64 v[6:7], v[12:13], 0, v[118:119]
	global_store_dword v[6:7], v1, off nt
	v_fmac_f32_e32 v5, v39, v3
	v_mul_f32_e32 v1, v39, v0
	v_cvt_pk_bf16_f32 v1, v5, v1
	v_lshl_add_u64 v[4:5], v[12:13], 0, v[120:121]
	v_fmac_f32_e32 v11, v8, v41
	v_mul_f32_e32 v8, v8, v17
	global_store_dword v[4:5], v1, off nt
	v_mul_f32_e32 v1, v40, v0
	v_fmac_f32_e32 v9, v40, v3
	v_cvt_pk_bf16_f32 v1, v9, v1
	v_lshl_add_u64 v[4:5], v[12:13], 0, v[122:123]
	v_mul_f32_e32 v0, v8, v0
	global_store_dword v[4:5], v1, off nt
	v_fmac_f32_e32 v11, v8, v3
	v_cvt_pk_bf16_f32 v2, v11, v0
	v_lshl_add_u64 v[0:1], v[12:13], 0, v[124:125]
	global_store_dword v[0:1], v2, off nt
	s_and_saveexec_b64 s[8:9], s[4:5]
	s_cbranch_execz .LBB0_359
	v_add_u32_e32 v12, 0x1000, v142
	ds_read2_b64 v[0:3], v12 offset1:32
	ds_read2_b64 v[4:7], v12 offset0:64 offset1:96
	ds_read2_b64 v[8:11], v12 offset0:128 offset1:160
	ds_read2_b64 v[12:15], v12 offset0:192 offset1:224
	s_waitcnt lgkmcnt(3)
	v_fma_f32 v16, 0, v0, v1
	v_pk_mul_f32 v[0:1], v[0:1], v[2:3]
	v_fma_f32 v2, v2, v16, v3
	s_waitcnt lgkmcnt(2)
	v_fma_f32 v2, v4, v2, v5
	v_fma_f32 v2, v6, v2, v7
	s_waitcnt lgkmcnt(1)
	v_fma_f32 v3, v8, v2, v9
	v_mov_b32_e32 v2, v0
	v_mov_b32_e32 v16, v4
	v_mov_b32_e32 v17, v10
	v_pk_mul_f32 v[0:1], v[0:1], v[4:5]
	v_pk_fma_f32 v[2:3], v[2:3], v[16:17], v[10:11]
	v_pk_mul_f32 v[0:1], v[0:1], v[6:7]
	s_waitcnt lgkmcnt(0)
	v_mov_b32_e32 v9, v12
	v_mov_b32_e32 v1, v3
	v_pk_mul_f32 v[2:3], v[0:1], v[8:9]
	v_pk_fma_f32 v[0:1], v[0:1], v[8:9], v[12:13]
	v_pk_mul_f32 v[2:3], v[2:3], v[10:11]
	v_mov_b32_e32 v4, v12
	v_mov_b32_e32 v0, v2
	v_mov_b32_e32 v5, v14
	v_pk_mul_f32 v[2:3], v[2:3], v[12:13]
	v_pk_fma_f32 v[0:1], v[0:1], v[4:5], v[14:15]
	v_pk_mul_f32 v[2:3], v[2:3], v[14:15]
	v_add_u32_e32 v0, 64, v92
	v_mov_b32_e32 v3, v1
	v_ashrrev_i32_e32 v1, 31, v0
	v_lshl_add_u64 v[0:1], v[0:1], 3, s[24:25]
	global_store_dwordx2 v[0:1], v[2:3], off

.LBB0_369:
	ds_read_b64 v[224:225], v1
	ds_read_b64 v[226:227], v1 offset:256
	ds_read_b64 v[228:229], v1 offset:512
	ds_read_b64 v[230:231], v1 offset:768
	ds_read_b64 v[232:233], v1 offset:1024
	ds_read_b64 v[234:235], v1 offset:1280
	ds_read_b64 v[236:237], v1 offset:1536
	s_waitcnt lgkmcnt(6)
	v_mul_f32_e32 v0, v0, v224
	v_fma_f32 v3, v3, v224, v225
	s_cmp_eq_u32 s7, 1
	s_cbranch_scc1 .Lscan_done_0
	s_waitcnt lgkmcnt(5)
	v_mul_f32_e32 v0, v0, v226
	v_fma_f32 v3, v3, v226, v227
	s_cmp_eq_u32 s7, 2
	s_cbranch_scc1 .Lscan_done_0
	s_waitcnt lgkmcnt(4)
	v_mul_f32_e32 v0, v0, v228
	v_fma_f32 v3, v3, v228, v229
	s_cmp_eq_u32 s7, 3
	s_cbranch_scc1 .Lscan_done_0
	s_waitcnt lgkmcnt(3)
	v_mul_f32_e32 v0, v0, v230
	v_fma_f32 v3, v3, v230, v231
	s_cmp_eq_u32 s7, 4
	s_cbranch_scc1 .Lscan_done_0
	s_waitcnt lgkmcnt(2)
	v_mul_f32_e32 v0, v0, v232
	v_fma_f32 v3, v3, v232, v233
	s_cmp_eq_u32 s7, 5
	s_cbranch_scc1 .Lscan_done_0
	s_waitcnt lgkmcnt(1)
	v_mul_f32_e32 v0, v0, v234
	v_fma_f32 v3, v3, v234, v235
	s_cmp_eq_u32 s7, 6
	s_cbranch_scc1 .Lscan_done_0
	s_waitcnt lgkmcnt(0)
	v_mul_f32_e32 v0, v0, v236
	v_fma_f32 v3, v3, v236, v237
.Lscan_done_0:
	s_waitcnt lgkmcnt(0)
.LBB0_370:
	v_cndmask_b32_e64 v1, v13, 1.0, s[0:1]
	v_cndmask_b32_e64 v2, v10, 0, s[0:1]
	v_cndmask_b32_e64 v10, v42, v15, s[0:1]
	v_cndmask_b32_e64 v13, v17, v14, s[0:1]
	v_cndmask_b32_e64 v14, v46, v43, s[0:1]
	v_cndmask_b32_e64 v15, v44, v41, s[0:1]
	v_cndmask_b32_e64 v17, v49, v47, s[0:1]
	v_cndmask_b32_e64 v41, v48, v45, s[0:1]
	v_fmac_f32_e32 v18, v32, v2
	v_mul_f32_e32 v32, v1, v32
	v_fmac_f32_e32 v31, v33, v2
	v_mul_f32_e32 v33, v1, v33
	v_fmac_f32_e32 v30, v34, v2
	v_mul_f32_e32 v34, v1, v34
	v_fmac_f32_e32 v29, v35, v2
	v_mul_f32_e32 v1, v1, v35
	v_fmac_f32_e32 v27, v37, v13
	v_mul_f32_e32 v35, v37, v10
	v_fmac_f32_e32 v24, v40, v15
	v_mul_f32_e32 v37, v40, v14
	v_fmac_f32_e32 v9, v4, v41
	v_mul_f32_e32 v40, v4, v17
	v_mul_f32_e32 v4, v32, v0
	v_fmac_f32_e32 v18, v32, v3
	v_cvt_pk_bf16_f32 v4, v18, v4
	v_fmac_f32_e32 v19, v20, v13
	v_mul_f32_e32 v2, v20, v10
	v_fmac_f32_e32 v28, v36, v13
	v_mul_f32_e32 v20, v36, v10
	v_fmac_f32_e32 v26, v38, v13
	v_mul_f32_e32 v10, v38, v10
	v_fmac_f32_e32 v23, v12, v15
	v_mul_f32_e32 v38, v12, v14
	v_lshl_add_u64 v[12:13], v[94:95], 0, s[60:61]
	global_store_dword v[96:97], v4, off offset:384 nt
	v_mul_f32_e32 v4, v33, v0
	v_fmac_f32_e32 v21, v22, v15
	v_mul_f32_e32 v22, v22, v14
	v_fmac_f32_e32 v25, v39, v15
	v_mul_f32_e32 v36, v39, v14
	v_fmac_f32_e32 v31, v33, v3
	v_cvt_pk_bf16_f32 v4, v31, v4
	v_lshl_add_u64 v[14:15], v[12:13], 0, v[88:89]
	global_store_dword v[14:15], v4, off nt
	v_mul_f32_e32 v4, v34, v0
	v_lshl_add_u64 v[14:15], v[12:13], 0, v[98:99]
	v_fmac_f32_e32 v29, v1, v3
	v_mul_f32_e32 v1, v1, v0
	v_fmac_f32_e32 v30, v34, v3
	v_cvt_pk_bf16_f32 v4, v30, v4
	global_store_dword v[14:15], v4, off nt
	v_cvt_pk_bf16_f32 v1, v29, v1
	v_lshl_add_u64 v[14:15], v[12:13], 0, v[100:101]
	global_store_dword v[14:15], v1, off nt
	v_mul_f32_e32 v1, v2, v0
	v_fmac_f32_e32 v19, v2, v3
	v_cvt_pk_bf16_f32 v1, v19, v1
	v_lshl_add_u64 v[14:15], v[12:13], 0, v[102:103]
	global_store_dword v[14:15], v1, off nt
	v_mul_f32_e32 v1, v20, v0
	v_fmac_f32_e32 v28, v20, v3
	v_cvt_pk_bf16_f32 v1, v28, v1
	v_lshl_add_u64 v[14:15], v[12:13], 0, v[104:105]
	global_store_dword v[14:15], v1, off nt
	v_mul_f32_e32 v1, v35, v0
	v_fmac_f32_e32 v27, v35, v3
	v_cvt_pk_bf16_f32 v1, v27, v1
	v_lshl_add_u64 v[14:15], v[12:13], 0, v[106:107]
	global_store_dword v[14:15], v1, off nt
	v_mul_f32_e32 v1, v10, v0
	v_fmac_f32_e32 v26, v10, v3
	v_cvt_pk_bf16_f32 v1, v26, v1
	v_lshl_add_u64 v[14:15], v[12:13], 0, v[108:109]
	global_store_dword v[14:15], v1, off nt
	v_mul_f32_e32 v1, v22, v0
	v_fmac_f32_e32 v21, v22, v3
	v_cvt_pk_bf16_f32 v1, v21, v1
	v_lshl_add_u64 v[14:15], v[12:13], 0, v[110:111]
	global_store_dword v[14:15], v1, off nt
	v_mul_f32_e32 v1, v36, v0
	v_fmac_f32_e32 v25, v36, v3
	v_cvt_pk_bf16_f32 v1, v25, v1
	v_lshl_add_u64 v[14:15], v[12:13], 0, v[112:113]
	global_store_dword v[14:15], v1, off nt
	v_mul_f32_e32 v1, v37, v0
	v_fmac_f32_e32 v24, v37, v3
	v_cvt_pk_bf16_f32 v1, v24, v1
	v_lshl_add_u64 v[14:15], v[12:13], 0, v[114:115]
	global_store_dword v[14:15], v1, off nt
	v_mul_f32_e32 v1, v38, v0
	v_fmac_f32_e32 v6, v16, v41
	v_mul_f32_e32 v16, v16, v17
	v_fmac_f32_e32 v23, v38, v3
	v_cvt_pk_bf16_f32 v1, v23, v1
	v_lshl_add_u64 v[14:15], v[12:13], 0, v[116:117]
	global_store_dword v[14:15], v1, off nt
	v_fmac_f32_e32 v6, v16, v3
	v_mul_f32_e32 v1, v16, v0
	v_fmac_f32_e32 v5, v7, v41
	v_mul_f32_e32 v39, v7, v17
	v_cvt_pk_bf16_f32 v1, v6, v1
	v_lshl_add_u64 v[6:7], v[12:13], 0, v[118:119]
	global_store_dword v[6:7], v1, off nt
	v_fmac_f32_e32 v5, v39, v3
	v_mul_f32_e32 v1, v39, v0
	v_cvt_pk_bf16_f32 v1, v5, v1
	v_lshl_add_u64 v[4:5], v[12:13], 0, v[120:121]
	v_fmac_f32_e32 v11, v8, v41
	v_mul_f32_e32 v8, v8, v17
	global_store_dword v[4:5], v1, off nt
	v_mul_f32_e32 v1, v40, v0
	v_fmac_f32_e32 v9, v40, v3
	v_cvt_pk_bf16_f32 v1, v9, v1
	v_lshl_add_u64 v[4:5], v[12:13], 0, v[122:123]
	v_mul_f32_e32 v0, v8, v0
	global_store_dword v[4:5], v1, off nt
	v_fmac_f32_e32 v11, v8, v3
	v_cvt_pk_bf16_f32 v2, v11, v0
	v_lshl_add_u64 v[0:1], v[12:13], 0, v[124:125]
	global_store_dword v[0:1], v2, off nt
	s_and_saveexec_b64 s[0:1], s[4:5]
	s_cbranch_execz .LBB0_300
	v_add_u32_e32 v12, 0x1800, v142
	ds_read2_b64 v[0:3], v12 offset1:32
	ds_read2_b64 v[4:7], v12 offset0:64 offset1:96
	ds_read2_b64 v[8:11], v12 offset0:128 offset1:160
	ds_read2_b64 v[12:15], v12 offset0:192 offset1:224
	s_waitcnt lgkmcnt(3)
	v_fma_f32 v16, 0, v0, v1
	v_pk_mul_f32 v[0:1], v[0:1], v[2:3]
	v_fma_f32 v2, v2, v16, v3
	s_waitcnt lgkmcnt(2)
	v_fma_f32 v2, v4, v2, v5
	v_fma_f32 v2, v6, v2, v7
	s_waitcnt lgkmcnt(1)
	v_fma_f32 v3, v8, v2, v9
	v_mov_b32_e32 v2, v0
	v_mov_b32_e32 v16, v4
	v_mov_b32_e32 v17, v10
	v_pk_mul_f32 v[0:1], v[0:1], v[4:5]
	v_pk_fma_f32 v[2:3], v[2:3], v[16:17], v[10:11]
	v_pk_mul_f32 v[0:1], v[0:1], v[6:7]
	s_waitcnt lgkmcnt(0)
	v_mov_b32_e32 v9, v12
	v_mov_b32_e32 v1, v3
	v_pk_mul_f32 v[2:3], v[0:1], v[8:9]
	v_pk_fma_f32 v[0:1], v[0:1], v[8:9], v[12:13]
	v_pk_mul_f32 v[2:3], v[2:3], v[10:11]
	v_mov_b32_e32 v4, v12
	v_mov_b32_e32 v0, v2
	v_mov_b32_e32 v5, v14
	v_pk_mul_f32 v[2:3], v[2:3], v[12:13]
	v_pk_fma_f32 v[0:1], v[0:1], v[4:5], v[14:15]
	v_pk_mul_f32 v[2:3], v[2:3], v[14:15]
	v_add_u32_e32 v0, 0x60, v92
	v_mov_b32_e32 v3, v1
	v_ashrrev_i32_e32 v1, 31, v0
	v_lshl_add_u64 v[0:1], v[0:1], 3, s[24:25]
	global_store_dwordx2 v[0:1], v[2:3], off
	s_branch .LBB0_300
